# ffn2 K-rotation key (m&7)*256 + (n&1)*128 (half-slot offset between neighbouring n-tiles), on v38
# speedup vs baseline: 1.0028x; 1.0028x over previous
.LBB0_126:
	s_lshr_b32 s15, s14, 3
	v_mov_b32_e32 v6, v254
	s_and_b32 s16, s15, 0xffffff8
	s_and_b32 s15, s14, 7
	v_ashrrev_i32_e32 v0, 3, v6
	s_lshl_b32 s83, s16, 7
	s_lshl_b32 s14, s14, 4
	v_xor_b32_e32 v5, v0, v6
	s_sub_i32 s14, s14, s83
	v_lshlrev_b32_e32 v1, 3, v5
	s_and_b32 s22, s14, 0xffffff80
	v_and_b32_e32 v7, 56, v1
	v_ashrrev_i32_e32 v1, 31, v0
	s_or_b32 s17, s16, s15
	s_ashr_i32 s23, s22, 31
	v_lshlrev_b64 v[2:3], 12, v[0:1]
	s_lshl_b32 s26, s17, 7
	s_lshl_b64 s[36:37], s[22:23], 13
	s_mov_b64 s[16:17], -1
	s_and_b64 vcc, exec, s[40:41]
	v_lshlrev_b64 v[2:3], 1, v[2:3]
	v_lshlrev_b32_e32 v148, 1, v7
	v_lshlrev_b32_e32 v7, 4, v6
	s_cbranch_vccz .LBB0_128
	s_lshl_b64 s[16:17], s[26:27], 13
	s_add_u32 s16, s25, s16
	s_addc_u32 s17, s33, s17
	s_lshl_b32 s14, s26, 1
	s_and_b32 s14, s14, 0x700
	s_and_b32 s84, s22, 0x80
	s_or_b32 s14, s14, s84
	s_add_u32 s16, s16, s14
	s_addc_u32 s17, s17, 0
	v_lshlrev_b32_e32 v85, 4, v6
	s_add_u32 s40, s44, s36
	v_lshl_add_u64 v[8:9], s[16:17], 0, v[2:3]
	v_readfirstlane_b32 s14, v85
	v_add_u32_e32 v14, 0x1000, v85
	s_addc_u32 s41, s45, s37
	s_lshl_b32 s84, s26, 1
	s_and_b32 s84, s84, 0x700
	s_and_b32 s85, s22, 0x80
	s_or_b32 s84, s84, s85
	s_add_u32 s40, s40, s84
	s_addc_u32 s41, s41, 0
	v_lshl_add_u64 v[8:9], v[8:9], 0, v[148:149]
	s_mov_b32 m0, s14
	s_mov_b64 s[16:17], 0x40000
	v_readfirstlane_b32 s14, v14
	v_add_u32_e32 v14, 0x2000, v85
	v_lshl_add_u64 v[10:11], s[40:41], 0, v[2:3]
	s_barrier
	global_load_lds_dwordx4 v[8:9], off
	v_lshl_add_u64 v[12:13], v[8:9], 0, s[16:17]
	s_mov_b32 m0, s14
	s_mov_b64 s[40:41], 0x80000
	v_readfirstlane_b32 s14, v14
	global_load_lds_dwordx4 v[12:13], off
	v_lshl_add_u64 v[12:13], v[8:9], 0, s[40:41]
	s_mov_b32 m0, s14
	s_mov_b64 s[84:85], 0xc0000
	global_load_lds_dwordx4 v[12:13], off
	v_add_u32_e32 v12, 0x3000, v85
	v_lshl_add_u64 v[8:9], v[8:9], 0, s[84:85]
	v_readfirstlane_b32 s14, v12
	s_mov_b32 m0, s14
	v_add_u32_e32 v12, 0x5000, v85
	global_load_lds_dwordx4 v[8:9], off
	v_add_u32_e32 v8, 0x4000, v85
	v_lshl_add_u64 v[10:11], v[10:11], 0, v[148:149]
	v_readfirstlane_b32 s14, v8
	s_mov_b32 m0, s14
	v_readfirstlane_b32 s14, v12
	v_add_u32_e32 v12, 0x6000, v85
	global_load_lds_dwordx4 v[10:11], off
	v_lshl_add_u64 v[8:9], v[10:11], 0, s[16:17]
	s_mov_b32 m0, s14
	v_readfirstlane_b32 s14, v12
	global_load_lds_dwordx4 v[8:9], off
	v_lshl_add_u64 v[8:9], v[10:11], 0, s[40:41]
	s_mov_b32 m0, s14
	s_mov_b64 s[16:17], 0
	global_load_lds_dwordx4 v[8:9], off
	v_lshl_add_u64 v[8:9], v[10:11], 0, s[84:85]
	v_add_u32_e32 v10, 0x7000, v85
	s_nop 0
	v_readfirstlane_b32 s14, v10
	s_mov_b32 m0, s14
	s_nop 0
	global_load_lds_dwordx4 v[8:9], off

.LBB0_130:
	s_add_u32 s14, s25, s30
	v_cmp_lt_i32_e32 vcc, -1, v4
	s_addc_u32 s17, s33, s31
	s_and_b64 s[30:31], vcc, exec
	v_lshrrev_b32_e32 v7, 4, v6
	v_and_b32_e32 v9, 7, v6
	s_cselect_b32 s31, s17, 0
	s_cselect_b32 s30, s14, 0
	s_add_u32 s28, s44, s28
	v_bfe_u32 v8, v6, 4, 2
	v_bitop3_b32 v7, v7, v9, 3 bitop3:0x6c
	s_addc_u32 s29, s45, s29
	v_lshlrev_b32_e32 v86, 4, v7
	v_bitop3_b32 v7, v8, v9, 4 bitop3:0x36
	v_and_b32_e32 v4, 15, v6
	v_lshlrev_b32_e32 v87, 4, v7
	v_lshrrev_b32_e32 v7, 1, v6
	s_cmp_lg_u64 s[30:31], 0
	v_and_or_b32 v4, v7, s47, v4
	v_lshl_add_u64 v[8:9], s[30:31], 0, v[148:149]
	s_cselect_b64 s[30:31], -1, 0
	s_lshl_b32 s14, s15, 7
	v_lshlrev_b32_e32 v88, 7, v4
	v_lshlrev_b32_e32 v4, 7, v6
	s_add_i32 s14, s83, s14
	s_mov_b32 s15, s27
	v_and_b32_e32 v89, 0x2780, v4
	v_lshl_add_u64 v[6:7], s[28:29], 0, v[148:149]
	v_lshlrev_b64 v[0:1], 13, v[0:1]
	v_lshlrev_b32_e32 v4, 4, v5
	s_lshl_b64 s[14:15], s[14:15], 13
	v_lshl_add_u64 v[64:65], v[8:9], 0, v[2:3]
	v_lshl_add_u64 v[66:67], v[6:7], 0, v[2:3]
	s_and_b32 s16, s56, 7
	s_lshl_b32 s16, s16, 8
	s_and_b32 s17, s56, 8
	s_lshl_b32 s17, s17, 4
	s_or_b32 s16, s16, s17
	v_mov_b32_e32 v10, s16
	v_mov_b32_e32 v11, 0
	v_lshl_add_u64 v[64:65], v[64:65], 0, v[10:11]
	v_lshl_add_u64 v[66:67], v[66:67], 0, v[10:11]
	v_lshl_add_u64 v[2:3], v[0:1], 0, s[36:37]
	v_and_b32_e32 v148, 0x70, v4
	v_lshl_add_u64 v[0:1], v[0:1], 0, s[14:15]
	s_mov_b64 s[40:41], 0x40000
	s_mov_b64 s[84:85], 0x80000
	s_mov_b64 s[86:87], 0xc0000
	v_lshl_add_u64 v[2:3], v[2:3], 0, v[148:149]
	v_or_b32_e32 v0, v0, v148
	v_mov_b32_e32 v56, 0
	s_mov_b32 s16, 0
	s_mov_b64 s[28:29], 0
	v_lshl_add_u64 v[68:69], v[64:65], 0, s[40:41]
	v_lshl_add_u64 v[70:71], v[64:65], 0, s[84:85]
	v_lshl_add_u64 v[72:73], v[64:65], 0, s[86:87]
	v_lshl_add_u64 v[74:75], v[66:67], 0, s[40:41]
	v_lshl_add_u64 v[76:77], v[66:67], 0, s[84:85]
	v_lshl_add_u64 v[78:79], v[66:67], 0, s[86:87]
	v_lshl_add_u64 v[80:81], s[10:11], 0, v[2:3]
	v_lshl_add_u64 v[82:83], s[10:11], 0, v[0:1]
	s_mov_b32 s17, 0
	v_mov_b32_e32 v57, v56
	v_mov_b32_e32 v58, v56
	v_mov_b32_e32 v59, v56
	v_mov_b32_e32 v0, v56
	v_mov_b32_e32 v1, v56
	v_mov_b32_e32 v2, v56
	v_mov_b32_e32 v3, v56
	v_mov_b32_e32 v4, v56
	v_mov_b32_e32 v5, v56
	v_mov_b32_e32 v6, v56
	v_mov_b32_e32 v7, v56
	v_mov_b32_e32 v8, v56
	v_mov_b32_e32 v9, v56
	v_mov_b32_e32 v10, v56
	v_mov_b32_e32 v11, v56
	v_mov_b32_e32 v12, v56
	v_mov_b32_e32 v13, v56
	v_mov_b32_e32 v14, v56
	v_mov_b32_e32 v15, v56
	v_mov_b32_e32 v16, v56
	v_mov_b32_e32 v17, v56
	v_mov_b32_e32 v18, v56
	v_mov_b32_e32 v19, v56
	v_mov_b32_e32 v20, v56
	v_mov_b32_e32 v21, v56
	v_mov_b32_e32 v22, v56
	v_mov_b32_e32 v23, v56
	v_mov_b32_e32 v24, v56
	v_mov_b32_e32 v25, v56
	v_mov_b32_e32 v26, v56
	v_mov_b32_e32 v27, v56
	v_mov_b32_e32 v28, v56
	v_mov_b32_e32 v29, v56
	v_mov_b32_e32 v30, v56
	v_mov_b32_e32 v31, v56
	v_mov_b32_e32 v32, v56
	v_mov_b32_e32 v33, v56
	v_mov_b32_e32 v34, v56
	v_mov_b32_e32 v35, v56
	v_mov_b32_e32 v36, v56
	v_mov_b32_e32 v37, v56
	v_mov_b32_e32 v38, v56
	v_mov_b32_e32 v39, v56
	s_waitcnt vmcnt(0)
	v_mov_b32_e32 v40, v56
	v_mov_b32_e32 v41, v56
	v_mov_b32_e32 v42, v56
	v_mov_b32_e32 v43, v56
	v_mov_b32_e32 v44, v56
	v_mov_b32_e32 v45, v56
	v_mov_b32_e32 v46, v56
	v_mov_b32_e32 v47, v56
	v_mov_b32_e32 v48, v56
	v_mov_b32_e32 v49, v56
	v_mov_b32_e32 v50, v56
	v_mov_b32_e32 v51, v56
	v_mov_b32_e32 v52, v56
	v_mov_b32_e32 v53, v56
	v_mov_b32_e32 v54, v56
	v_mov_b32_e32 v55, v56
	v_mov_b32_e32 v60, v56
	v_mov_b32_e32 v61, v56
	v_mov_b32_e32 v62, v56
	v_mov_b32_e32 v63, v56
	s_branch .LBB0_132

.LBB0_136:
	s_andn2_b64 vcc, exec, s[14:15]
	s_cbranch_vccnz .LBB0_131
	s_add_i32 s14, s16, 0x8000
	s_and_b32 s14, s14, 0x8000
	v_add_u32_e32 v94, s14, v85
	s_lshl_b32 s15, s26, 1
	s_and_b32 s15, s15, 0x700
	v_readfirstlane_b32 s14, v94
	s_mov_b32 m0, s14
	s_and_b32 s14, s22, 0x80
	s_or_b32 s15, s15, s14
	s_add_u32 s14, s15, s28
	s_add_u32 s14, s14, 0x80
	s_and_b32 s14, s14, 0x1fff
	s_add_u32 s14, s14, 0x1201000
	s_mov_b32 s15, 0
	v_lshl_add_u64 v[92:93], v[82:83], 0, s[14:15]
	s_sub_u32 s14, s14, 0x800000
	v_lshl_add_u64 v[90:91], v[80:81], 0, s[14:15]
	global_load_lds_dwordx4 v[92:93], off
	s_add_u32 m0, m0, 0x1000
	v_lshl_add_u64 v[92:93], v[92:93], 0, s[40:41]
	global_load_lds_dwordx4 v[92:93], off
	s_add_u32 m0, m0, 0x1000
	v_lshl_add_u64 v[92:93], v[92:93], 0, s[40:41]
	global_load_lds_dwordx4 v[92:93], off
	s_add_u32 m0, m0, 0x1000
	v_lshl_add_u64 v[92:93], v[92:93], 0, s[40:41]
	global_load_lds_dwordx4 v[92:93], off
	s_add_u32 m0, m0, 0x1000
	s_nop 0
	global_load_lds_dwordx4 v[90:91], off
	s_add_u32 m0, m0, 0x1000
	v_lshl_add_u64 v[90:91], v[90:91], 0, s[40:41]
	global_load_lds_dwordx4 v[90:91], off
	s_add_u32 m0, m0, 0x1000
	v_lshl_add_u64 v[90:91], v[90:91], 0, s[40:41]
	global_load_lds_dwordx4 v[90:91], off
	s_add_u32 m0, m0, 0x1000
	v_lshl_add_u64 v[90:91], v[90:91], 0, s[40:41]
	global_load_lds_dwordx4 v[90:91], off
	s_branch .LBB0_131
